# v76 = v75 + select: dead km LDS staging loop and its two workgroup barriers removed (km now only read through SGPRs)
# baseline (speedup 1.0000x reference)
.LBB0_164:
	s_ashr_i32 s0, s33, 1
	s_ashr_i32 s1, s0, 31
	s_lshl_b64 s[10:11], s[0:1], 12
	v_readlane_b32 s28, v254, 61
	v_readlane_b32 s29, v254, 62
	s_nop 0
	s_add_u32 s28, s28, s10
	s_addc_u32 s29, s29, s11
	s_and_b32 s1, s33, 1
	v_lshl_or_b32 v0, s1, 7, v69
	v_or_b32_e32 v0, s10, v0
	v_mov_b32_e32 v1, s11
	v_lshlrev_b64 v[0:1], 7, v[0:1]
	v_lshl_add_u64 v[0:1], s[64:65], 0, v[0:1]
	s_waitcnt lgkmcnt(0)
	global_load_dwordx4 v[60:63], v[0:1], off
	global_load_dwordx4 v[56:59], v[0:1], off offset:16
	global_load_dwordx4 v[52:55], v[0:1], off offset:32
	global_load_dwordx4 v[48:51], v[0:1], off offset:48
	global_load_dwordx4 v[44:47], v[0:1], off offset:64
	global_load_dwordx4 v[40:43], v[0:1], off offset:80
	global_load_dwordx4 v[36:39], v[0:1], off offset:96
	global_load_dwordx4 v[32:35], v[0:1], off offset:112
	s_lshl_b32 s0, s0, 4
	s_lshl_b32 s34, s1, 1
	s_ashr_i32 s1, s0, 31
	v_readlane_b32 s12, v254, 57
	s_lshl_b64 s[6:7], s[0:1], 2
	v_readlane_b32 s22, v255, 3
	v_readlane_b32 s13, v254, 58
	v_readlane_b32 s23, v255, 4
	s_add_u32 s12, s22, s6
	v_readlane_b32 s14, v254, 59
	v_readlane_b32 s24, v255, 5
	s_addc_u32 s13, s23, s7
	s_lshl_b64 s[0:1], s[0:1], 13
	v_readlane_b32 s15, v254, 60
	v_readlane_b32 s20, v255, 1
	v_readlane_b32 s25, v255, 6
	s_add_u32 s14, s24, s0
	s_addc_u32 s15, s25, s1
	s_mov_b32 s20, 0
	v_readlane_b32 s16, v254, 61
	v_readlane_b32 s17, v254, 62
	v_readlane_b32 s18, v254, 63
	v_readlane_b32 s19, v255, 0
	v_readlane_b32 s21, v255, 2
	v_readlane_b32 s26, v255, 7
	v_readlane_b32 s27, v255, 8
	s_branch .LBB0_168
